# LDS bank conflicts: same 4-bit K-tile swizzle in the neighbourhood and dilated attention loops
# speedup vs baseline: 1.0024x; 1.0002x over previous
; __device__ __forceinline__ int crow(int r, int hi) { return (r & 3) + 8 * (r >> 2) + 4 * hi; }
; __device__ __forceinline__ int v_st(int k, int c) { const int kk = (k & ~0xC) | ((k & 4) << 1) | ((k & 8) >> 1); return ((kk >> 3) * 4 + (c >> 5)) * 512 + ((kk & 7) * 32 + (c & 31)) * 2; }
; __device__ __forceinline__ int v_rd_base(int lane) { return ((lane & 3) << 3) | (((lane >> 2) & 3) << 6) | (((lane >> 4) & 1) << 5) | (((lane >> 5) & 1) << 8); }
; template <int MODE>
; __device__ __forceinline__ void amask(f32x16& p0, f32x16& p1, int j, const Unit& U, int wid, int r32, int hi, const float* tbl) {
;     ...
;       const int jq = (wid & 1) * 32 + r32, cs = min(max(jq - 8, 0), 48);
;       const float* tr = tbl + (kr - qrow + 7) * 31 + (15 - jq);
; #pragma unroll
;       for (int r2 = 0; r2 < 8; ++r2) {
;         float b0[2], b1[2];
; #pragma unroll
;         for (int q = 0; q < 2; ++q) { const int c = crow(r2 * 2 + q, hi); b0[q] = tr[c]; b1[q] = tr[c + 32]; }
;         asm volatile("" ::: "memory");
; #pragma unroll
;         for (int q = 0; q < 2; ++q) { const int r = r2 * 2 + q, c = crow(r, hi);
;           p0[r] = ((unsigned)(c - cs) < 16u) ? p0[r] + b0[q] : NEG;
;           p1[r] = ((unsigned)(c + 32 - cs) < 16u) ? p1[r] + b1[q] : NEG; }
; template <int MODE, int SDEPTH, bool SIMPLE>
; __device__ __forceinline__ void attn_body(const Unit& U, char* lds, const int tid) {
;     ...
;   const bf16_t* Qw = U.Q + (long)(wid * QBLK + r32) * U.ldq + hi * 8;
; #pragma unroll
;   for (int d0 = 0; d0 < 8; ++d0) qr[d0] = *reinterpret_cast<const bf16x8*>(Qw + d0 * 16);
;   const int sr = tid >> 4, sc = (tid & 15) * 8, vst0 = v_st(sr, sc), vst1 = v_st(32 + sr, sc);
;   const int vb0 = (int)(uintptr_t)V_lds + v_rd_base(lane);
;   const bf16_t* Kh = U.K; const bf16_t* Vh = U.V; const int LDK = U.ldk;
;   struct { bf16x8 vs0, vs1, ks0, ks1; } sr_[SDEPTH];
.LBB0_284:
	s_or_b64 exec, exec, s[0:1]
	s_ashr_i32 s8, s17, 8
	s_ashr_i32 s9, s8, 31
	s_min_u32 s0, s2, 0x78
	s_lshl_b64 s[2:3], s[8:9], 13
	s_lshl_b32 s9, s4, 6
	s_or_b32 s20, s2, s9
	s_mul_i32 s9, s3, 0x8c00
	s_mul_hi_u32 s24, s20, 0x8c00
	s_max_u32 s1, s4, 4
	s_add_i32 s24, s24, s9
	s_mul_i32 s9, s20, 0x8c00
	s_add_u32 s26, s10, s9
	v_mov_b32_e32 v0, v146
	s_addc_u32 s24, s11, s24
	s_add_i32 s9, 0, 0x11800
	v_and_b32_e32 v1, 0x3fffffc0, v0
	v_lshl_add_u32 v157, v1, 2, s9
	v_lshlrev_b32_e32 v1, 3, v0
	s_lshl_b32 s27, s27, 7
	s_sub_i32 s0, s0, s1
	v_ashrrev_i32_e32 v158, 6, v0
	v_and_b32_e32 v154, 63, v0
	v_and_b32_e32 v1, 0x78, v1
	v_and_b32_e32 v159, 31, v0
	v_bfe_u32 v156, v0, 5, 1
	v_lshlrev_b32_e32 v155, 5, v158
	s_mov_b32 s28, 0
	s_cmp_lt_i32 s0, -11
	v_cmp_gt_u32_e64 s[38:39], 32, v154
	v_lshlrev_b32_e32 v192, 1, v1
	s_cbranch_scc1 .LBB0_295
	s_lshl_b32 s1, s1, 6
	s_max_u32 s15, s15, 4
	s_lshr_b32 s9, s17, 5
	s_min_u32 s25, s25, 0x78
	s_addk_i32 s1, 0xff00
	s_add_u32 s1, s2, s1
	s_addc_u32 s2, s3, 0
	s_lshl_b32 s36, s27, 1
	s_add_u32 s40, s26, s36
	s_mul_i32 s2, s2, 0x8c00
	s_mul_hi_u32 s37, s1, 0x8c00
	s_addc_u32 s41, s24, 0
	s_add_i32 s37, s37, s2
	s_mul_i32 s1, s1, 0x8c00
	s_add_u32 s1, s10, s1
	s_addc_u32 s2, s11, s37
	s_add_u32 s42, s1, s36
	s_addc_u32 s43, s2, 0
	s_add_u32 s44, s42, 0x1000
	v_or_b32_e32 v4, v155, v159
	v_mov_b64_e32 v[2:3], s[40:41]
	s_addc_u32 s45, s43, 0
	s_add_i32 s2, s0, 11
	v_mad_i64_i32 v[2:3], s[0:1], v4, s14, v[2:3]
	v_lshlrev_b32_e32 v150, 4, v156
	v_mov_b32_e32 v151, v193
	v_lshl_add_u64 v[2:3], v[2:3], 0, v[150:151]
	global_load_dwordx4 v[98:101], v[2:3], off
	global_load_dwordx4 v[102:105], v[2:3], off offset:32
	global_load_dwordx4 v[106:109], v[2:3], off offset:64
	global_load_dwordx4 v[110:113], v[2:3], off offset:96
	global_load_dwordx4 v[114:117], v[2:3], off offset:128
	global_load_dwordx4 v[118:121], v[2:3], off offset:160
	global_load_dwordx4 v[122:125], v[2:3], off offset:192
	global_load_dwordx4 v[126:129], v[2:3], off offset:224
	v_lshlrev_b32_e32 v3, 4, v154
	v_lshlrev_b32_e32 v2, 3, v154
	v_and_b32_e32 v3, 0xc0, v3
	v_lshlrev_b32_e32 v4, 1, v154
	v_and_or_b32 v3, v2, 24, v3
	v_and_b32_e32 v4, 32, v4
	v_and_b32_e32 v2, 0x100, v2
	s_cmp_lg_u32 0, -1
	v_or3_b32 v2, v3, v4, v2
	s_cselect_b32 s0, 0, 0
	v_ashrrev_i32_e32 v10, 4, v0
	v_add_u32_e32 v65, s0, v2
	s_and_b32 s0, s9, 7
	s_mul_i32 s37, s5, 0x1f0
	s_lshl_b32 s9, s0, 8
	s_mul_i32 s0, s15, 0x230000
	v_add_u32_e32 v11, 32, v10
	s_movk_i32 s5, 0x4600
	s_add_i32 vcc_lo, s0, 0xff740000
	v_mad_i64_i32 v[2:3], s[0:1], v11, s5, 0
	v_or_b32_e32 v2, v2, v1
	v_mad_i64_i32 v[6:7], s[0:1], v10, s5, 0
	v_lshlrev_b64 v[2:3], 1, v[2:3]
	v_or_b32_e32 v6, v6, v1
	v_lshl_add_u64 v[4:5], s[42:43], 0, v[2:3]
	v_lshlrev_b64 v[6:7], 1, v[6:7]
	v_lshl_add_u64 v[2:3], s[44:45], 0, v[2:3]
	v_lshl_add_u64 v[8:9], s[42:43], 0, v[6:7]
	global_load_dwordx4 v[134:137], v[4:5], off offset:2048
	global_load_dwordx4 v[130:133], v[8:9], off offset:2048
	v_lshl_add_u64 v[4:5], s[44:45], 0, v[6:7]
	global_load_dwordx4 v[142:145], v[2:3], off
	global_load_dwordx4 v[138:141], v[4:5], off
	v_lshrrev_b32_e32 v2, 1, v10
	v_and_b32_e32 v3, 3, v10
	v_and_or_b32 v2, v2, 4, v3
	v_lshlrev_b32_e32 v3, 1, v11
	v_and_b32_e32 v4, 0xfffff0, v11
	v_and_or_b32 v3, v3, 8, v4
	v_lshlrev_b32_e32 v4, 1, v10
	v_and_b32_e32 v5, 0xfffff0, v10
	v_and_or_b32 v4, v4, 8, v5
	v_lshrrev_b32_e32 v3, 1, v3
	v_lshrrev_b32_e32 v1, 5, v1
	v_lshrrev_b32_e32 v4, 1, v4
	v_or_b32_e32 v3, v3, v1
	v_or_b32_e32 v1, v4, v1
	v_lshl_add_u32 v2, v2, 6, 0
	v_lshl_add_u32 v17, v1, 9, v2
	v_lshl_add_u32 v18, v3, 9, v2
	v_lshlrev_b32_e32 v2, 4, v159
	v_and_b32_e32 v2, 0x70, v2
	v_lshlrev_b32_e32 v249, 3, v159
	v_and_b32_e32 v249, 0x80, v249
	v_or_b32_e32 v2, v2, v249
	v_or_b32_e32 v3, 32, v150
	v_xad_u32 v24, v3, v2, 0
	v_or_b32_e32 v3, 64, v150
	v_xad_u32 v25, v3, v2, 0
	v_or_b32_e32 v3, 0x60, v150
	v_xad_u32 v26, v3, v2, 0
	v_or_b32_e32 v3, 0x80, v150
	v_xad_u32 v27, v3, v2, 0
	v_or_b32_e32 v3, 0xa0, v150
	v_xad_u32 v28, v3, v2, 0
	v_or_b32_e32 v3, 0xc0, v150
	v_xad_u32 v29, v3, v2, 0
	v_or_b32_e32 v3, 0xe0, v150
	v_xad_u32 v23, v150, v2, 0
	v_xad_u32 v30, v3, v2, 0
	v_and_or_b32 v2, v155, 32, v159
	v_sub_u32_e64 v2, v2, 8 clamp
	v_min_u32_e32 v2, 48, v2
	v_lshlrev_b32_e32 v3, 2, v156
	v_sub_u32_e32 v4, v3, v2
	v_cmp_gt_u32_e64 s[40:41], 16, v4
	v_and_b32_e32 v4, -16, v4
	s_movk_i32 s5, 0xffe0
	v_cmp_eq_u32_e64 s[42:43], s5, v4
	v_or_b32_e32 v4, 1, v3
	v_sub_u32_e32 v4, v4, v2
	v_cmp_gt_u32_e64 s[44:45], 16, v4
	v_and_b32_e32 v4, -16, v4
	v_cmp_eq_u32_e64 s[46:47], s5, v4
	v_or_b32_e32 v4, 2, v3
	v_sub_u32_e32 v4, v4, v2
	v_cmp_gt_u32_e64 s[48:49], 16, v4
	v_and_b32_e32 v4, -16, v4
	v_cmp_eq_u32_e64 s[50:51], s5, v4
	v_or_b32_e32 v4, 3, v3
	v_sub_u32_e32 v4, v4, v2
; __device__ __forceinline__ int crow(int r, int hi) { return (r & 3) + 8 * (r >> 2) + 4 * hi; }
; __device__ __forceinline__ int v_st(int k, int c) { const int kk = (k & ~0xC) | ((k & 4) << 1) | ((k & 8) >> 1); return ((kk >> 3) * 4 + (c >> 5)) * 512 + ((kk & 7) * 32 + (c & 31)) * 2; }
; __device__ __forceinline__ int v_rd_base(int lane) { return ((lane & 3) << 3) | (((lane >> 2) & 3) << 6) | (((lane >> 4) & 1) << 5) | (((lane >> 5) & 1) << 8); }
; template <int MODE>
; __device__ __forceinline__ void amask(f32x16& p0, f32x16& p1, int j, const Unit& U, int wid, int r32, int hi, const float* tbl) {
;     ...
;       const int jq = (wid & 1) * 32 + r32, cs = min(max(jq - 8, 0), 48);
;       const float* tr = tbl + (kr - qrow + 7) * 31 + (15 - jq);
; #pragma unroll
;       for (int r2 = 0; r2 < 8; ++r2) {
;         float b0[2], b1[2];
; #pragma unroll
;         for (int q = 0; q < 2; ++q) { const int c = crow(r2 * 2 + q, hi); b0[q] = tr[c]; b1[q] = tr[c + 32]; }
;         asm volatile("" ::: "memory");
; #pragma unroll
;         for (int q = 0; q < 2; ++q) { const int r = r2 * 2 + q, c = crow(r, hi);
;           p0[r] = ((unsigned)(c - cs) < 16u) ? p0[r] + b0[q] : NEG;
;           p1[r] = ((unsigned)(c + 32 - cs) < 16u) ? p1[r] + b1[q] : NEG; }
; template <int MODE, int SDEPTH, bool SIMPLE>
; __device__ __forceinline__ void attn_body(const Unit& U, char* lds, const int tid) {
;     ...
;   float m_reg = -1e30f, l_reg = 0; f32x16 o[4] = {}; bf16x8 qr[8];
;   const bf16_t* Qw = U.Q + (long)(wid * QBLK + r32) * U.ldq + hi * 8;
; #pragma unroll
;   for (int d0 = 0; d0 < 8; ++d0) qr[d0] = *reinterpret_cast<const bf16x8*>(Qw + d0 * 16);
;   const int sr = tid >> 4, sc = (tid & 15) * 8, vst0 = v_st(sr, sc), vst1 = v_st(32 + sr, sc);
;   const int vb0 = (int)(uintptr_t)V_lds + v_rd_base(lane);
;   const bf16_t* Kh = U.K; const bf16_t* Vh = U.V; const int LDK = U.ldk;
;   struct { bf16x8 vs0, vs1, ks0, ks1; } sr_[SDEPTH];
	v_cmp_gt_u32_e64 s[52:53], 16, v4
	v_and_b32_e32 v4, -16, v4
	v_cmp_eq_u32_e64 s[54:55], s5, v4
	v_or_b32_e32 v4, 8, v3
	v_sub_u32_e32 v4, v4, v2
	v_cmp_gt_u32_e64 s[56:57], 16, v4
	v_and_b32_e32 v4, -16, v4
	v_cmp_eq_u32_e64 s[58:59], s5, v4
	v_or_b32_e32 v4, 9, v3
	v_sub_u32_e32 v4, v4, v2
	v_cmp_gt_u32_e64 s[60:61], 16, v4
	v_and_b32_e32 v4, -16, v4
	v_cmp_eq_u32_e64 s[62:63], s5, v4
	v_or_b32_e32 v4, 10, v3
	v_sub_u32_e32 v4, v4, v2
	v_cmp_gt_u32_e64 s[64:65], 16, v4
	v_and_b32_e32 v4, -16, v4
	v_cmp_eq_u32_e64 s[66:67], s5, v4
	v_or_b32_e32 v4, 11, v3
	v_sub_u32_e32 v4, v4, v2
	s_mov_b32 s23, s68
	v_cmp_gt_u32_e64 s[68:69], 16, v4
	v_and_b32_e32 v4, -16, v4
	s_mov_b64 s[6:7], s[70:71]
	v_cmp_eq_u32_e64 s[70:71], s5, v4
	v_or_b32_e32 v4, 16, v3
	v_sub_u32_e32 v4, v4, v2
	v_cmp_gt_u32_e64 s[72:73], 16, v4
	v_and_b32_e32 v4, -16, v4
	v_cmp_eq_u32_e64 s[74:75], s5, v4
	v_or_b32_e32 v4, 17, v3
	v_sub_u32_e32 v4, v4, v2
	v_cmp_gt_u32_e64 s[76:77], 16, v4
	v_and_b32_e32 v4, -16, v4
	v_bitop3_b32 v19, v192, v0, s79 bitop3:0x78
	v_lshrrev_b32_e32 v249, 1, v0
	v_and_b32_e32 v249, 0x80, v249
	v_xor_b32_e32 v19, v19, v249
	v_cmp_eq_u32_e64 s[78:79], s5, v4
	v_or_b32_e32 v4, 18, v3
	v_sub_u32_e32 v4, v4, v2
	v_cmp_gt_u32_e64 s[80:81], 16, v4
	v_and_b32_e32 v4, -16, v4
	v_cmp_eq_u32_e64 s[82:83], s5, v4
	v_or_b32_e32 v4, 19, v3
	v_sub_u32_e32 v4, v4, v2
	v_cmp_gt_u32_e64 s[84:85], 16, v4
	v_and_b32_e32 v4, -16, v4
	v_cmp_eq_u32_e64 s[86:87], s5, v4
	v_or_b32_e32 v4, 24, v3
	v_sub_u32_e32 v4, v4, v2
	v_cmp_gt_u32_e64 s[88:89], 16, v4
	v_and_b32_e32 v4, -16, v4
	v_cmp_eq_u32_e64 s[90:91], s5, v4
	v_or_b32_e32 v4, 25, v3
	v_sub_u32_e32 v4, v4, v2
	v_cmp_gt_u32_e64 s[92:93], 16, v4
	v_and_b32_e32 v4, -16, v4
	v_ashrrev_i32_e32 v1, 7, v0
	v_cmp_eq_u32_e64 s[94:95], s5, v4
	v_or_b32_e32 v4, 26, v3
	v_or_b32_e32 v3, 27, v3
	v_sub_u32_e32 v4, v4, v2
	v_sub_u32_e32 v2, v3, v2
	v_add_u32_e32 v3, s4, v1
	v_max_i32_e32 v3, 4, v3
	s_mul_i32 s36, s15, 0x7c
	v_cmp_gt_u32_e64 s[96:97], 16, v4
	v_and_b32_e32 v4, -16, v4
	v_cmp_gt_u32_e64 s[0:1], 16, v2
	v_and_b32_e32 v2, -16, v2
	v_add_u32_e32 v3, -4, v3
	v_cmp_eq_u32_e64 s[98:99], s5, v4
	v_cmp_eq_u32_e64 s[4:5], s5, v2
	v_lshlrev_b32_e32 v2, 2, v159
	v_min_u32_e32 v160, 0x78, v3
	v_add_u32_e32 v3, s36, v150
	s_movk_i32 s36, 0x7c
	v_add_u32_e32 v151, v157, v2
	v_sub_u32_e32 v2, v3, v2
	v_mul_lo_u32 v1, v1, s36
	v_sub_u32_e32 v1, v2, v1
	v_lshlrev_b32_e32 v2, 1, v0
	v_and_b32_e32 v2, 0x80, v2
	v_sub_u32_e32 v1, v1, v2
	v_subrev_u32_e32 v1, s37, v1
	s_add_i32 s36, 0, 0x122b0
	v_add_u32_e32 v162, s36, v1
	s_mul_hi_i32 s36, s8, 0x11800000
	s_mul_i32 s8, s8, 0x11800000
	s_or_b32 s8, s8, s9
	v_mov_b32_e32 v2, s8
	v_mov_b32_e32 v3, s36
	s_sub_i32 s25, s25, s15
	v_mad_i64_i32 v[2:3], s[8:9], v10, s14, v[2:3]
	s_add_i32 s25, s25, 12
	v_readlane_b32 s8, v250, 4
	v_and_b32_e32 v0, 15, v0
	s_add_u32 s8, s8, vcc_lo
	v_readlane_b32 s9, v250, 5
	v_and_b32_e32 v16, 48, v192
	v_lshl_add_u32 v20, v10, 8, 0
	v_lshl_add_u32 v21, v11, 8, 0
	v_lshlrev_b32_e32 v22, 8, v159
	v_lshl_or_b32 v2, v0, 4, v2
	s_addc_u32 s9, s9, 0
	v_mov_b32_e32 v14, v193
	v_mov_b32_e32 v15, v193
	v_lshl_add_u64 v[152:153], s[8:9], 0, v[2:3]
	v_mov_b32_e32 v0, v193
	v_mov_b32_e32 v1, v193
	v_mov_b32_e32 v2, v193
	v_mov_b32_e32 v3, v193
	v_mov_b32_e32 v4, v193
	v_mov_b32_e32 v5, v193
	v_mov_b32_e32 v6, v193
	v_mov_b32_e32 v7, v193
	v_mov_b32_e32 v8, v193
	v_mov_b32_e32 v9, v193
	v_mov_b32_e32 v10, v193
	v_mov_b32_e32 v11, v193
	v_mov_b32_e32 v12, v193
	v_mov_b32_e32 v13, v193
	v_add_u32_e32 v164, v17, v16
	v_add_u32_e32 v165, v18, v16
	v_add_u32_e32 v166, v20, v19
	v_add_u32_e32 v167, v21, v19
	v_add_u32_e32 v168, v23, v22
	v_add_u32_e32 v169, v24, v22
	v_add_u32_e32 v170, v25, v22
	v_add_u32_e32 v171, v26, v22
	v_add_u32_e32 v172, v27, v22
	v_add_u32_e32 v173, v28, v22
	v_add_u32_e32 v174, v29, v22
	v_add_u32_e32 v175, v30, v22
	v_mov_b64_e32 v[62:63], v[14:15]
	v_mov_b64_e32 v[46:47], v[14:15]
	v_mov_b64_e32 v[30:31], v[14:15]
	v_add_u32_e32 v161, 8, v160
	v_mov_b32_e32 v64, 0
	v_mov_b32_e32 v163, 0xf149f2ca
	v_mov_b64_e32 v[60:61], v[12:13]
	v_mov_b64_e32 v[58:59], v[10:11]
	v_mov_b64_e32 v[56:57], v[8:9]
	v_mov_b64_e32 v[54:55], v[6:7]
	v_mov_b64_e32 v[52:53], v[4:5]
	v_mov_b64_e32 v[50:51], v[2:3]
	v_mov_b64_e32 v[48:49], v[0:1]
	v_mov_b64_e32 v[44:45], v[12:13]
	v_mov_b64_e32 v[42:43], v[10:11]
	v_mov_b64_e32 v[40:41], v[8:9]
	v_mov_b64_e32 v[38:39], v[6:7]
	v_mov_b64_e32 v[36:37], v[4:5]
	v_mov_b64_e32 v[34:35], v[2:3]
	v_mov_b64_e32 v[32:33], v[0:1]
	v_mov_b64_e32 v[28:29], v[12:13]
	v_mov_b64_e32 v[26:27], v[10:11]
	v_mov_b64_e32 v[24:25], v[8:9]
	v_mov_b64_e32 v[22:23], v[6:7]
	v_mov_b64_e32 v[20:21], v[4:5]
	v_mov_b64_e32 v[18:19], v[2:3]
	v_mov_b64_e32 v[16:17], v[0:1]
	s_branch .LBB0_289

; __global__ void __launch_bounds__(512) mega(Args a) {
;     ...
;         const int qbi = un & 31, hg = (un >> 5) & 3, b = (un >> 7) & 1, g = un >> 8;
;         const int dil = g == 0 ? 1 : (g == 1 ? 4 : 16), L = SEQ / dil, npc = L / 256, c = qbi / npc, i0 = (qbi % npc) * 256;
;         const int k0 = max(i0 - 64, 0), kend = min(i0 + 320, L), head = g * 4 + hg;
;         __syncthreads();
;         att::Unit U{};
;         const size_t tq = (size_t)b * SEQ + (size_t)i0 * dil + c, tk = (size_t)b * SEQ + (size_t)k0 * dil + c;
;         U.Q = PROJ + tq * NIN + C_QC + head * 128; U.K = PROJ + tk * NIN + C_KC + head * 128; U.V = PROJ + tk * NIN + C_VC + head * 128;
;         U.ldq = NIN * dil; U.ldk = NIN * dil; U.NT = (kend - k0) >> 6;
;         U.O = OC + ((size_t)g * MT + tq) * 512 + hg * 128; U.ldo = 512 * dil;
;         U.LSE = LSE + ((size_t)g * MT + tq) * 4 + hg; U.ldl = 4 * dil;
;         U.i0 = i0; U.k0 = k0; U.slope = exp2f(-8.f * (float)(head + 1) / 12.f) * (float)dil * att::ISCALE;
.LBB0_301:
	s_and_b32 s3, s22, 31
	s_bfe_u32 s27, s22, 0x20005
	s_ashr_i32 s38, s22, 8
	s_cmp_eq_u32 s38, 1
	s_cselect_b64 s[4:5], -1, 0
	s_and_b64 s[0:1], s[4:5], exec
	s_cselect_b32 s2, 2, 4
	s_cmpk_lt_u32 s22, 0x100
	s_cselect_b64 s[8:9], -1, 0
	s_and_b64 s[0:1], s[8:9], exec
	s_cselect_b32 s0, 0, s2
	s_lshr_b32 s15, 32, s0
	s_sub_i32 s2, 5, s0
	s_add_i32 s15, s15, -1
	s_lshr_b32 s2, s3, s2
	s_and_b32 s3, s15, s3
	s_lshl_b32 s3, s3, 8
	s_lshr_b32 s1, 0x2000, s0
	s_add_i32 s15, s3, 0x140
	s_min_u32 s1, s15, s1
	s_lshl_b32 s15, s22, 6
	v_sub_u32_e64 v0, s3, 64 clamp
	s_and_b32 s15, s15, 0x2000
	s_lshl_b32 s0, s3, s0
	v_readfirstlane_b32 s40, v0
	s_add_i32 s0, s0, s15
	s_or_b32 s41, s0, s2
	s_sub_i32 s0, s1, s40
	v_mov_b32_e32 v0, v146
	s_barrier
	s_ashr_i32 s39, s0, 6
	s_add_i32 s0, 0, 0x11800
	v_ashrrev_i32_e32 v157, 6, v0
	v_and_b32_e32 v1, 0x3fffffc0, v0
	v_and_b32_e32 v158, 31, v0
	v_lshl_add_u32 v156, v1, 2, s0
	v_lshlrev_b32_e32 v154, 5, v157
	v_lshlrev_b32_e32 v1, 3, v0
	v_and_b32_e32 v147, 63, v0
	v_or_b32_e32 v148, v154, v158
	v_and_b32_e32 v1, 0x78, v1
	v_bfe_u32 v155, v0, 5, 1
	v_ashrrev_i32_e32 v149, 31, v148
	s_mov_b32 s42, 0
	s_cmp_lt_i32 s39, 1
	v_cmp_gt_u32_e64 s[36:37], 32, v147
	v_lshl_add_u32 v159, v158, 2, v156
	v_lshlrev_b32_e32 v192, 1, v1
	s_cbranch_scc1 .LBB0_316
	s_lshr_b32 s0, s22, 5
	s_and_b32 s0, s0, 3
	s_and_b32 s26, s21, 0x2000
	s_lshl_b32 s28, s0, 7
	s_and_b64 s[0:1], s[4:5], exec
	s_cselect_b32 s24, 4, 16
	s_and_b64 s[0:1], s[8:9], exec
	s_cselect_b32 s43, 1, s24
	s_lshl_b32 s0, s38, 2
	s_or_b32 s50, s0, s27
	s_and_b64 s[0:1], s[4:5], exec
	s_cselect_b32 s24, 2, 4
	s_and_b64 s[0:1], s[8:9], exec
	s_cselect_b32 s0, 0, s24
	s_lshl_b64 s[0:1], s[40:41], s0
	s_add_i32 s1, s0, s15
	s_or_b32 s1, s1, s2
	s_mul_i32 s24, s41, 0x8c00
	s_mul_hi_u32 s15, s41, 0x8c00
	s_add_u32 s44, s10, s24
	s_addc_u32 s15, s11, s15
	s_lshl_b32 s24, s50, 7
	s_ashr_i32 s25, s24, 31
	s_lshl_b64 s[24:25], s[24:25], 1
	s_add_u32 s44, s44, s24
	s_addc_u32 s45, s15, s25
	s_mul_hi_u32 s15, s1, 0x8c00
	s_mul_i32 s1, s1, 0x8c00
	s_add_u32 s1, s10, s1
	s_addc_u32 s15, s11, s15
	s_add_u32 s1, s1, s24
	s_addc_u32 s15, s15, s25
	s_add_u32 s24, s1, 0x3000
	s_addc_u32 s25, s15, 0
	s_add_u32 s46, s1, 0x3c00
	s_addc_u32 s47, s15, 0
	s_and_b64 s[48:49], s[4:5], exec
	s_mov_b32 s1, 0x46000
	s_cselect_b32 s1, 0x11800, s1
	s_and_b64 s[48:49], s[8:9], exec
	s_cselect_b32 s15, 0x4600, s1
	s_add_i32 s50, s50, 1
	v_cvt_f32_i32_e32 v2, s50
	s_mov_b32 s1, 0x41400000
	v_ashrrev_i32_e32 v12, 4, v0
	v_bitop3_b32 v19, v192, v0, s79 bitop3:0x78
	v_lshrrev_b32_e32 v249, 1, v0
	v_and_b32_e32 v249, 0x80, v249
	v_xor_b32_e32 v19, v19, v249
	v_mul_f32_e32 v2, 0xc1000000, v2
	v_div_scale_f32 v3, s[48:49], s1, s1, v2
	v_rcp_f32_e32 v4, v3
	v_and_b32_e32 v0, 15, v0
	v_lshlrev_b32_e32 v0, 4, v0
	v_and_b32_e32 v16, 48, v192
	v_fma_f32 v5, -v3, v4, 1.0
	v_fmac_f32_e32 v4, v5, v4
	v_div_scale_f32 v5, vcc, v2, s1, v2
	v_mul_f32_e32 v6, v5, v4
	v_fma_f32 v7, -v3, v6, v5
	v_fmac_f32_e32 v6, v7, v4
	v_fma_f32 v3, -v3, v6, v5
	v_div_fmas_f32 v3, v3, v4, v6
	v_div_fixup_f32 v2, v3, s1, v2
	s_mov_b32 s1, 0xc2fc0000
	v_cmp_gt_f32_e32 vcc, s1, v2
	s_and_b64 s[48:49], vcc, exec
	s_cselect_b32 s1, 0xffffffc0, 0
	v_cndmask_b32_e32 v3, 0, v231, vcc
	v_add_f32_e32 v2, v2, v3
	v_exp_f32_e32 v2, v2
	v_cvt_f32_ubyte0_e32 v3, s43
	v_lshlrev_b32_e32 v4, 4, v155
	v_mov_b32_e32 v5, v193
	v_ldexp_f32 v2, v2, s1
	v_mul_f32_e32 v2, v2, v3
	v_mul_f32_e32 v65, 0x413504f3, v2
	v_mad_i64_i32 v[2:3], s[48:49], s15, v148, 0
	v_lshl_add_u64 v[2:3], v[2:3], 1, s[44:45]
	v_lshl_add_u64 v[2:3], v[2:3], 0, v[4:5]
	s_mov_b64 s[44:45], 0x2400
	s_movk_i32 s1, 0x2000
	v_lshl_add_u64 v[6:7], v[2:3], 0, s[44:45]
	v_add_co_u32_e32 v2, vcc, s1, v2
	v_lshlrev_b32_e32 v5, 1, v147
	s_nop 0
	v_addc_co_u32_e32 v3, vcc, 0, v3, vcc
	global_load_dwordx4 v[98:101], v[6:7], off offset:32
	global_load_dwordx4 v[102:105], v[6:7], off offset:64
	global_load_dwordx4 v[106:109], v[6:7], off offset:96
	global_load_dwordx4 v[110:113], v[6:7], off offset:128
	global_load_dwordx4 v[114:117], v[6:7], off offset:160
	global_load_dwordx4 v[118:121], v[6:7], off offset:192
	global_load_dwordx4 v[122:125], v[2:3], off offset:1024
	global_load_dwordx4 v[126:129], v[6:7], off offset:224
	v_lshlrev_b32_e32 v3, 4, v147
	v_lshlrev_b32_e32 v2, 3, v147
	v_and_b32_e32 v3, 0xc0, v3
	v_and_or_b32 v3, v2, 24, v3
	v_and_b32_e32 v5, 32, v5
; __device__ __forceinline__ int crow(int r, int hi) { return (r & 3) + 8 * (r >> 2) + 4 * hi; }
; __device__ __forceinline__ int v_st(int k, int c) { const int kk = (k & ~0xC) | ((k & 4) << 1) | ((k & 8) >> 1); return ((kk >> 3) * 4 + (c >> 5)) * 512 + ((kk & 7) * 32 + (c & 31)) * 2; }
; __device__ __forceinline__ int v_rd_base(int lane) { return ((lane & 3) << 3) | (((lane >> 2) & 3) << 6) | (((lane >> 4) & 1) << 5) | (((lane >> 5) & 1) << 8); }
; template <int MODE>
; __device__ __forceinline__ void amask(f32x16& p0, f32x16& p1, int j, const Unit& U, int wid, int r32, int hi, const float* tbl) {
;     ...
;     const int base = U.k0 + j * 64 - (U.i0 + wid * 32 + r32);
; #pragma unroll
;     for (int r = 0; r < 16; ++r) { const int c = crow(r, hi); const int d0 = abs(base + c), d1 = abs(base + c + 32);
;       p0[r] = (d0 <= 64) ? p0[r] - U.slope * (float)d0 : NEG;
;       p1[r] = (d1 <= 64) ? p1[r] - U.slope * (float)d1 : NEG; }
; template <int MODE, int SDEPTH, bool SIMPLE>
; __device__ __forceinline__ void attn_body(const Unit& U, char* lds, const int tid) {
;     ...
;   const bf16_t* Qw = U.Q + (long)(wid * QBLK + r32) * U.ldq + hi * 8;
; #pragma unroll
;   for (int d0 = 0; d0 < 8; ++d0) qr[d0] = *reinterpret_cast<const bf16x8*>(Qw + d0 * 16);
;   const int sr = tid >> 4, sc = (tid & 15) * 8, vst0 = v_st(sr, sc), vst1 = v_st(32 + sr, sc);
;   const int vb0 = (int)(uintptr_t)V_lds + v_rd_base(lane);
;   const bf16_t* Kh = U.K; const bf16_t* Vh = U.V; const int LDK = U.ldk;
;   struct { bf16x8 vs0, vs1, ks0, ks1; } sr_[SDEPTH];
	v_and_b32_e32 v2, 0x100, v2
	s_cmp_lg_u32 0, -1
	v_or3_b32 v2, v3, v5, v2
	s_cselect_b32 s1, 0, 0
	v_add_u32_e32 v5, 32, v12
	v_add_u32_e32 v160, s1, v2
	v_mad_i64_i32 v[2:3], s[44:45], s15, v5, 0
	v_or_b32_e32 v2, v2, v1
	v_mad_i64_i32 v[8:9], s[44:45], s15, v12, 0
	v_lshlrev_b64 v[2:3], 1, v[2:3]
	v_or_b32_e32 v8, v8, v1
	v_lshl_add_u64 v[6:7], s[24:25], 0, v[2:3]
	v_lshlrev_b64 v[8:9], 1, v[8:9]
	v_lshl_add_u64 v[2:3], s[46:47], 0, v[2:3]
	v_lshl_add_u64 v[10:11], s[24:25], 0, v[8:9]
	global_load_dwordx4 v[134:137], v[6:7], off
	global_load_dwordx4 v[130:133], v[10:11], off
	v_lshl_add_u64 v[6:7], s[46:47], 0, v[8:9]
	global_load_dwordx4 v[142:145], v[2:3], off
	global_load_dwordx4 v[138:141], v[6:7], off
	v_lshrrev_b32_e32 v2, 1, v12
	v_and_b32_e32 v3, 3, v12
	v_and_or_b32 v2, v2, 4, v3
	v_lshlrev_b32_e32 v3, 1, v5
	v_and_b32_e32 v6, 0xfffff0, v5
	v_and_or_b32 v3, v3, 8, v6
	v_lshlrev_b32_e32 v6, 1, v12
	v_and_b32_e32 v7, 0xfffff0, v12
	v_and_or_b32 v6, v6, 8, v7
	v_lshrrev_b32_e32 v3, 1, v3
	v_lshrrev_b32_e32 v1, 5, v1
	v_lshrrev_b32_e32 v6, 1, v6
	v_or_b32_e32 v3, v3, v1
	v_or_b32_e32 v1, v6, v1
	v_lshl_add_u32 v2, v2, 6, 0
	v_lshl_add_u32 v17, v1, 9, v2
	v_lshlrev_b32_e32 v1, 4, v158
	v_lshl_add_u32 v18, v3, 9, v2
	v_and_b32_e32 v1, 0x70, v1
	v_lshlrev_b32_e32 v249, 3, v158
	v_and_b32_e32 v249, 0x80, v249
	v_or_b32_e32 v1, v1, v249
	v_or_b32_e32 v2, 32, v4
	v_xad_u32 v24, v2, v1, 0
	v_or_b32_e32 v2, 64, v4
	v_xad_u32 v25, v2, v1, 0
	v_or_b32_e32 v2, 0x60, v4
	v_xad_u32 v26, v2, v1, 0
	v_or_b32_e32 v2, 0x80, v4
	v_xad_u32 v27, v2, v1, 0
	v_or_b32_e32 v2, 0xa0, v4
	v_xad_u32 v28, v2, v1, 0
	v_or_b32_e32 v2, 0xc0, v4
	v_xad_u32 v29, v2, v1, 0
	v_or_b32_e32 v2, 0xe0, v4
	v_xad_u32 v30, v2, v1, 0
	v_add_u32_e32 v2, s3, v154
	s_min_u32 s1, s3, 64
	s_add_i32 s0, s0, s26
	v_xad_u32 v23, v4, v1, 0
	v_lshlrev_b32_e32 v1, 2, v155
	v_subrev_u32_e32 v162, 64, v2
	v_add_u32_e32 v163, 0x5f, v2
	v_add_u32_e32 v2, s1, v158
	s_add_i32 s0, s0, s2
	v_sub_u32_e32 v1, v1, v2
	s_mul_hi_u32 s1, s0, 0x8c00
	s_mul_i32 s0, s0, 0x8c00
	v_sub_u32_e32 v164, v1, v154
	s_lshl_b32 s3, s15, 1
	v_add_u32_e32 v1, 0x60, v12
	v_mov_b64_e32 v[2:3], s[0:1]
	v_lshl_add_u32 v21, v5, 8, 0
	v_add_u32_e32 v161, v156, v4
	v_mad_i64_i32 v[4:5], s[0:1], s3, v1, v[2:3]
	s_lshl_b32 s0, s38, 9
	s_or_b32 s0, s0, s28
	s_ashr_i32 s1, s0, 31
	s_lshl_b64 s[0:1], s[0:1], 1
	v_mov_b32_e32 v1, v193
	s_add_u32 s0, s74, s0
	v_lshl_add_u64 v[4:5], v[4:5], 0, v[0:1]
	s_addc_u32 s1, s75, s1
	v_lshl_add_u64 v[150:151], s[0:1], 0, v[4:5]
	v_add_u32_e32 v4, 64, v12
	v_mad_i64_i32 v[2:3], s[2:3], s3, v4, v[2:3]
	v_lshl_add_u32 v20, v12, 8, 0
	v_lshlrev_b32_e32 v22, 8, v158
	v_lshl_add_u64 v[0:1], v[2:3], 0, v[0:1]
	v_mov_b32_e32 v14, v193
	v_mov_b32_e32 v15, v193
	v_lshl_add_u64 v[152:153], s[0:1], 0, v[0:1]
	v_mov_b32_e32 v0, v193
	v_mov_b32_e32 v1, v193
	v_mov_b32_e32 v2, v193
	v_mov_b32_e32 v3, v193
	v_mov_b32_e32 v4, v193
	v_mov_b32_e32 v5, v193
	v_mov_b32_e32 v6, v193
	v_mov_b32_e32 v7, v193
	v_mov_b32_e32 v8, v193
	v_mov_b32_e32 v9, v193
	v_mov_b32_e32 v10, v193
	v_mov_b32_e32 v11, v193
	v_mov_b32_e32 v12, v193
	v_mov_b32_e32 v13, v193
	v_add_u32_e32 v166, v17, v16
	v_add_u32_e32 v167, v18, v16
	v_add_u32_e32 v168, v20, v19
	v_add_u32_e32 v169, v21, v19
	v_add_u32_e32 v170, v23, v22
	v_add_u32_e32 v171, v24, v22
	v_add_u32_e32 v172, v25, v22
	v_add_u32_e32 v173, v26, v22
	v_add_u32_e32 v174, v27, v22
	v_add_u32_e32 v175, v28, v22
	v_add_u32_e32 v176, v29, v22
	v_add_u32_e32 v177, v30, v22
	v_mov_b64_e32 v[62:63], v[14:15]
	v_mov_b64_e32 v[46:47], v[14:15]
	v_mov_b64_e32 v[30:31], v[14:15]
	s_lshl_b32 s28, s15, 7
	v_mov_b32_e32 v64, 0
	v_mov_b32_e32 v165, 0xf149f2ca
	v_mov_b64_e32 v[60:61], v[12:13]
	v_mov_b64_e32 v[58:59], v[10:11]
	v_mov_b64_e32 v[56:57], v[8:9]
	v_mov_b64_e32 v[54:55], v[6:7]
	v_mov_b64_e32 v[52:53], v[4:5]
	v_mov_b64_e32 v[50:51], v[2:3]
	v_mov_b64_e32 v[48:49], v[0:1]
	v_mov_b64_e32 v[44:45], v[12:13]
	v_mov_b64_e32 v[42:43], v[10:11]
	v_mov_b64_e32 v[40:41], v[8:9]
	v_mov_b64_e32 v[38:39], v[6:7]
	v_mov_b64_e32 v[36:37], v[4:5]
	v_mov_b64_e32 v[34:35], v[2:3]
	v_mov_b64_e32 v[32:33], v[0:1]
	v_mov_b64_e32 v[28:29], v[12:13]
	v_mov_b64_e32 v[26:27], v[10:11]
	v_mov_b64_e32 v[24:25], v[8:9]
	v_mov_b64_e32 v[22:23], v[6:7]
	v_mov_b64_e32 v[20:21], v[4:5]
	v_mov_b64_e32 v[18:19], v[2:3]
	v_mov_b64_e32 v[16:17], v[0:1]
	s_mov_b32 s43, 0
	s_branch .LBB0_306
